# v21: v18 + P0 x->bf16 units store dwordx4 (lane pairs exchange halves by DPP quad_perm) instead of dwordx2
# baseline (speedup 1.0000x reference)
; #define LAS __attribute__((address_space(3)))
; __global__ void __launch_bounds__(512, 2) fwd_megakernel(Args a) {
;     ...
;     for (int rep = 0; rep < (EXP == 3 ? 2 : 1); ++rep) {
;         LAS float* scr = (LAS float*)(lds + wave * 16384);
;         constexpr int I1 = 32 * 320, I2 = 48 * 64, I3 = 32 * 256, I4 = 32 * 64, I5 = 4 * 4 * 8;
;         for (int it = gw; it < I1 + I2 + I3 + I4 + I5; it += NGW) {
;             int r = it;
;             if (r < I1) { const int kb = r / 320, nb = r % 320; transpose_item(w_in_ab, 10240, 64 * kb, 32 * nb, WT1, 2048, 32 * nb, scr, lane); continue; } r -= I1;
;             if (r < I2) { const int kb = r / 64, nb = r % 64; transpose_item(w_out_ab, 2048, 64 * kb, 32 * nb, WT2, 3072, 32 * nb, scr, lane); continue; } r -= I2;
;             if (r < I3) { const int kb = r / 256, nb = r % 256; const int n0 = 32 * nb, part = n0 >> 11, chn = n0 & 2047;
;                 const int type = (part == 0 || part == 3) ? 1 : 0, bj = (part >= 2) ? 1 : 0;
;                 const int drow = 256 * (2 * (chn >> 7) + type) + 128 * bj + (chn & 127);
;                 transpose_item(w_in_c, 8192, 64 * kb, n0, WT3, 2048, drow, scr, lane); continue; } r -= I3;
;             if (r < I4) { const int kb = r / 64, nb = r % 64; transpose_item(w_out_c, 2048, 64 * kb, 32 * nb, WT4, 2048, 32 * nb, scr, lane); continue; } r -= I4;
;             { const int gi = r >> 5, rr = r & 31, kb = rr >> 3, nb = rr & 7; transpose_item(pool_w + (size_t)gi * 65536, 256, 64 * kb, 32 * nb, WT5, 256, gi * 256 + 32 * nb, scr, lane); }
;     ...
;         for (size_t i = gt; i < (size_t)MT * DM / 8; i += (size_t)NGT * 4) {
;             f32x4 v0[4], v1[4];
; #pragma unroll
;             for (int u = 0; u < 4; ++u) { const size_t ii = i + (size_t)u * NGT; if (ii < (size_t)MT * DM / 8) { const size_t e = ii * 8; const float* src = e < (size_t)MP * DM ? x_prompt + e : x_sample + (e - (size_t)MP * DM);
;                 v0[u] = *(const f32x4*)src; v1[u] = *(const f32x4*)(src + 4); } }
; #pragma unroll
;             for (int u = 0; u < 4; ++u) { const size_t ii = i + (size_t)u * NGT; if (ii < (size_t)MT * DM / 8) { const size_t e = ii * 8;
;                 u32x4 o; o.x = pk2(v0[u][0], v0[u][1]); o.y = pk2(v0[u][2], v0[u][3]); o.z = pk2(v1[u][0], v1[u][1]); o.w = pk2(v1[u][2], v1[u][3]);
;                 *(u32x4*)(XB + e) = o; } } }
.LBB0_3:
	s_or_b64 exec, exec, s[2:3]
	s_load_dwordx16 s[44:59], s[0:1], 0x0
	s_lshr_b32 s0, s14, 6
	s_add_u32 s2, s92, 0x6000000
	s_addc_u32 s3, s93, 0
	s_add_u32 s4, s92, 0x8800000
	s_addc_u32 s5, s93, 0
	v_writelane_b32 v255, s4, 14
	v_lshlrev_b32_e32 v201, 3, v168
	s_waitcnt lgkmcnt(0)
	v_writelane_b32 v255, s5, 15
	s_add_u32 s4, s92, 0x9400000
	s_addc_u32 s5, s93, 0
	v_writelane_b32 v255, s4, 16
	s_barrier
	s_nop 0
	v_writelane_b32 v255, s5, 17
	s_add_u32 s4, s92, 0xb400000
	s_addc_u32 s5, s93, 0
	v_writelane_b32 v255, s4, 18
	s_add_u32 s8, s92, 0xbc00000
	s_addc_u32 s9, s93, 0
	v_writelane_b32 v255, s5, 19
	s_nop 0
	v_readlane_b32 s1, v255, 13
	s_lshl_b32 s1, s1, 3
	s_add_i32 s6, s0, s1
	v_writelane_b32 v255, s1, 20
	s_nop 0
	v_readlane_b32 s4, v255, 9
	v_readlane_b32 s5, v255, 10
	s_lshl_b32 s4, s4, 3
	v_writelane_b32 v255, s4, 21
	s_cmpk_gt_i32 s6, 0x5c7f
	s_nop 0
	v_writelane_b32 v255, s5, 22
	s_mov_b32 s4, s6
	v_writelane_b32 v255, s4, 23
	s_nop 1
	v_writelane_b32 v255, s5, 24
	v_readlane_b32 s60, v255, 23
	v_readlane_b32 s61, v255, 21
	v_readlane_b32 s82, v255, 2
	v_readlane_b32 s83, v255, 3
	v_readlane_b32 s84, v255, 14
	v_readlane_b32 s85, v255, 15
	v_readlane_b32 s86, v255, 16
	v_readlane_b32 s87, v255, 17
	v_readlane_b32 s88, v255, 18
	v_readlane_b32 s89, v255, 19
	v_and_b32_e32 v1, 63, v168
	v_readfirstlane_b32 s90, v168
	v_and_b32_e32 v252, 15, v1
	v_lshlrev_b32_e32 v2, 4, v252
	v_lshrrev_b32_e32 v253, 4, v1
	v_lshlrev_b32_e32 v68, 4, v253
	v_lshrrev_b32_e32 v69, 3, v1
	v_and_b32_e32 v254, 7, v1
	v_lshlrev_b32_e32 v128, 4, v254
	v_lshlrev_b32_e32 v170, 3, v1
	v_lshlrev_b32_e32 v171, 4, v1
	s_lshr_b32 s90, s90, 6
	s_lshl_b32 s90, s90, 13
	v_lshlrev_b32_e32 v180, 1, v253
	v_and_b32_e32 v181, 7, v252
	v_xor_b32_e32 v180, v180, v181
	v_lshlrev_b32_e32 v180, 4, v180
	v_lshl_add_u32 v180, v252, 9, v180
	v_add_u32_e32 v180, s90, v180
	v_xor_b32_e32 v181, 16, v180
	v_lshrrev_b32_e32 v252, 5, v1
	v_xor_b32_e32 v252, v254, v252
	v_lshlrev_b32_e32 v252, 4, v252
	v_lshl_add_u32 v252, v69, 7, v252
	v_add_u32_e32 v182, s90, v252
	v_xor_b32_e32 v200, 32, v182
	v_xor_b32_e32 v202, 64, v182
	v_xor_b32_e32 v203, 0x60, v182
	s_mov_b32 s36, 0xaaaaaaaa
	s_mov_b32 s37, 0xaaaaaaaa
	s_mov_b32 s38, 0x55555555
	s_mov_b32 s39, 0x55555555
	v_and_b32_e32 v252, 1, v1
	v_mul_u32_u24_e32 v252, 0x1f8, v252
	v_lshl_add_u32 v252, v1, 3, v252
	s_cmp_lt_u32 s60, 24128
	s_cbranch_scc0 .Lp0_done
	s_mov_b32 s62, s60
	s_cmp_lt_u32 s62, 11840
	s_cbranch_scc0 .Lp0_dx_a0
	s_mov_b32 s75, 1
	s_cmp_lt_u32 s62, 5120
	s_cbranch_scc0 .Lp0_d2_a0
	s_and_b32 s29, s62, 31
	s_lshr_b32 s30, s62, 5
	s_mul_i32 s31, s29, 2621440
	s_lshl_b32 s32, s30, 8
	s_add_u32 s31, s31, s32
	s_add_u32 s64, s50, s31
	s_addc_u32 s65, s51, 0
	s_mov_b32 s66, 40960
	s_mul_i32 s31, s30, 262144
	s_lshl_b32 s32, s29, 7
	s_add_u32 s31, s31, s32
	s_add_u32 s72, s2, s31
	s_addc_u32 s73, s3, 0
	s_movk_i32 s74, 0x1000
	s_branch .Lp0_dd_a0

; __device__ __forceinline__ unsigned pk2(float lo, float hi) { return f2bf(lo) | (f2bf(hi) << 16); }
; __global__ void __launch_bounds__(512, 2) fwd_megakernel(Args a) {
;     ...
;             for (int u = 0; u < 4; ++u) { const size_t ii = i + (size_t)u * NGT; if (ii < (size_t)MT * DM / 8) { const size_t e = ii * 8;
;                 u32x4 o; o.x = pk2(v0[u][0], v0[u][1]); o.y = pk2(v0[u][2], v0[u][3]); o.z = pk2(v1[u][0], v1[u][1]); o.w = pk2(v1[u][2], v1[u][3]);
;                 *(u32x4*)(XB + e) = o; } } }
.Lp0_px_a:
	v_cvt_pk_bf16_f32 v80, v80, v81
	v_cvt_pk_bf16_f32 v81, v82, v83
	v_cvt_pk_bf16_f32 v84, v84, v85
	s_mov_b64 vcc, s[36:37]
	v_cvt_pk_bf16_f32 v85, v86, v87
	v_cndmask_b32_dpp v82, v80, v84, vcc quad_perm:[1,0,3,2] row_mask:0xf bank_mask:0xf
	s_nop 0
	v_cndmask_b32_dpp v83, v81, v85, vcc quad_perm:[1,0,3,2] row_mask:0xf bank_mask:0xf
	s_mov_b64 vcc, s[38:39]
	s_nop 0
	v_cndmask_b32_dpp v80, v84, v80, vcc quad_perm:[1,0,3,2] row_mask:0xf bank_mask:0xf
	v_cndmask_b32_dpp v81, v85, v81, vcc quad_perm:[1,0,3,2] row_mask:0xf bank_mask:0xf
	global_store_dwordx4 v252, v[80:83], s[72:73] offset:0
	v_cvt_pk_bf16_f32 v92, v92, v93
	v_cvt_pk_bf16_f32 v93, v94, v95
	v_cvt_pk_bf16_f32 v96, v96, v97
	s_mov_b64 vcc, s[36:37]
	v_cvt_pk_bf16_f32 v97, v98, v99
	v_cndmask_b32_dpp v94, v92, v96, vcc quad_perm:[1,0,3,2] row_mask:0xf bank_mask:0xf
	s_nop 0
	v_cndmask_b32_dpp v95, v93, v97, vcc quad_perm:[1,0,3,2] row_mask:0xf bank_mask:0xf
	s_mov_b64 vcc, s[38:39]
	s_nop 0
	v_cndmask_b32_dpp v92, v96, v92, vcc quad_perm:[1,0,3,2] row_mask:0xf bank_mask:0xf
	v_cndmask_b32_dpp v93, v97, v93, vcc quad_perm:[1,0,3,2] row_mask:0xf bank_mask:0xf
	global_store_dwordx4 v252, v[92:95], s[72:73] offset:1024
	v_cvt_pk_bf16_f32 v100, v100, v101
	v_cvt_pk_bf16_f32 v101, v102, v103
	v_cvt_pk_bf16_f32 v104, v104, v105
	s_mov_b64 vcc, s[36:37]
	v_cvt_pk_bf16_f32 v105, v106, v107
	v_cndmask_b32_dpp v102, v100, v104, vcc quad_perm:[1,0,3,2] row_mask:0xf bank_mask:0xf
	s_nop 0
	v_cndmask_b32_dpp v103, v101, v105, vcc quad_perm:[1,0,3,2] row_mask:0xf bank_mask:0xf
	s_mov_b64 vcc, s[38:39]
	s_nop 0
	v_cndmask_b32_dpp v100, v104, v100, vcc quad_perm:[1,0,3,2] row_mask:0xf bank_mask:0xf
	v_cndmask_b32_dpp v101, v105, v101, vcc quad_perm:[1,0,3,2] row_mask:0xf bank_mask:0xf
	global_store_dwordx4 v252, v[100:103], s[72:73] offset:2048
	v_cvt_pk_bf16_f32 v108, v108, v109
	v_cvt_pk_bf16_f32 v109, v110, v111
	v_cvt_pk_bf16_f32 v112, v112, v113
	s_mov_b64 vcc, s[36:37]
	v_cvt_pk_bf16_f32 v113, v114, v115
	v_cndmask_b32_dpp v110, v108, v112, vcc quad_perm:[1,0,3,2] row_mask:0xf bank_mask:0xf
	s_nop 0
	v_cndmask_b32_dpp v111, v109, v113, vcc quad_perm:[1,0,3,2] row_mask:0xf bank_mask:0xf
	s_mov_b64 vcc, s[38:39]
	s_nop 0
	v_cndmask_b32_dpp v108, v112, v108, vcc quad_perm:[1,0,3,2] row_mask:0xf bank_mask:0xf
	v_cndmask_b32_dpp v109, v113, v109, vcc quad_perm:[1,0,3,2] row_mask:0xf bank_mask:0xf
	global_store_dwordx4 v252, v[108:111], s[72:73] offset:3072
	s_add_u32 s72, s72, 0x1000
	s_addc_u32 s73, s73, 0
	v_cvt_pk_bf16_f32 v116, v116, v117
	v_cvt_pk_bf16_f32 v117, v118, v119
	v_cvt_pk_bf16_f32 v136, v136, v137
	s_mov_b64 vcc, s[36:37]
	v_cvt_pk_bf16_f32 v137, v138, v139
	v_cndmask_b32_dpp v118, v116, v136, vcc quad_perm:[1,0,3,2] row_mask:0xf bank_mask:0xf
	s_nop 0
	v_cndmask_b32_dpp v119, v117, v137, vcc quad_perm:[1,0,3,2] row_mask:0xf bank_mask:0xf
	s_mov_b64 vcc, s[38:39]
	s_nop 0
	v_cndmask_b32_dpp v116, v136, v116, vcc quad_perm:[1,0,3,2] row_mask:0xf bank_mask:0xf
	v_cndmask_b32_dpp v117, v137, v117, vcc quad_perm:[1,0,3,2] row_mask:0xf bank_mask:0xf
	global_store_dwordx4 v252, v[116:119], s[72:73] offset:0
	v_cvt_pk_bf16_f32 v140, v140, v141
	v_cvt_pk_bf16_f32 v141, v142, v143
	v_cvt_pk_bf16_f32 v144, v144, v145
	s_mov_b64 vcc, s[36:37]
	v_cvt_pk_bf16_f32 v145, v146, v147
	v_cndmask_b32_dpp v142, v140, v144, vcc quad_perm:[1,0,3,2] row_mask:0xf bank_mask:0xf
	s_nop 0
	v_cndmask_b32_dpp v143, v141, v145, vcc quad_perm:[1,0,3,2] row_mask:0xf bank_mask:0xf
	s_mov_b64 vcc, s[38:39]
	s_nop 0
	v_cndmask_b32_dpp v140, v144, v140, vcc quad_perm:[1,0,3,2] row_mask:0xf bank_mask:0xf
	v_cndmask_b32_dpp v141, v145, v141, vcc quad_perm:[1,0,3,2] row_mask:0xf bank_mask:0xf
	global_store_dwordx4 v252, v[140:143], s[72:73] offset:1024
	v_cvt_pk_bf16_f32 v148, v148, v149
	v_cvt_pk_bf16_f32 v149, v150, v151
	v_cvt_pk_bf16_f32 v152, v152, v153
	s_mov_b64 vcc, s[36:37]
	v_cvt_pk_bf16_f32 v153, v154, v155
	v_cndmask_b32_dpp v150, v148, v152, vcc quad_perm:[1,0,3,2] row_mask:0xf bank_mask:0xf
	s_nop 0
	v_cndmask_b32_dpp v151, v149, v153, vcc quad_perm:[1,0,3,2] row_mask:0xf bank_mask:0xf
	s_mov_b64 vcc, s[38:39]
	s_nop 0
	v_cndmask_b32_dpp v148, v152, v148, vcc quad_perm:[1,0,3,2] row_mask:0xf bank_mask:0xf
	v_cndmask_b32_dpp v149, v153, v149, vcc quad_perm:[1,0,3,2] row_mask:0xf bank_mask:0xf
	global_store_dwordx4 v252, v[148:151], s[72:73] offset:2048
	v_cvt_pk_bf16_f32 v156, v156, v157
	v_cvt_pk_bf16_f32 v157, v158, v159
	v_cvt_pk_bf16_f32 v160, v160, v161
	s_mov_b64 vcc, s[36:37]
	v_cvt_pk_bf16_f32 v161, v162, v163
	v_cndmask_b32_dpp v158, v156, v160, vcc quad_perm:[1,0,3,2] row_mask:0xf bank_mask:0xf
	s_nop 0
	v_cndmask_b32_dpp v159, v157, v161, vcc quad_perm:[1,0,3,2] row_mask:0xf bank_mask:0xf
	s_mov_b64 vcc, s[38:39]
	s_nop 0
	v_cndmask_b32_dpp v156, v160, v156, vcc quad_perm:[1,0,3,2] row_mask:0xf bank_mask:0xf
	v_cndmask_b32_dpp v157, v161, v157, vcc quad_perm:[1,0,3,2] row_mask:0xf bank_mask:0xf
	global_store_dwordx4 v252, v[156:159], s[72:73] offset:3072

; __device__ __forceinline__ unsigned pk2(float lo, float hi) { return f2bf(lo) | (f2bf(hi) << 16); }
; __global__ void __launch_bounds__(512, 2) fwd_megakernel(Args a) {
;     ...
;             for (int u = 0; u < 4; ++u) { const size_t ii = i + (size_t)u * NGT; if (ii < (size_t)MT * DM / 8) { const size_t e = ii * 8;
;                 u32x4 o; o.x = pk2(v0[u][0], v0[u][1]); o.y = pk2(v0[u][2], v0[u][3]); o.z = pk2(v1[u][0], v1[u][1]); o.w = pk2(v1[u][2], v1[u][3]);
;                 *(u32x4*)(XB + e) = o; } } }
.Lp0_px_b:
	v_cvt_pk_bf16_f32 v184, v184, v185
	v_cvt_pk_bf16_f32 v185, v186, v187
	v_cvt_pk_bf16_f32 v188, v188, v189
	s_mov_b64 vcc, s[36:37]
	v_cvt_pk_bf16_f32 v189, v190, v191
	v_cndmask_b32_dpp v186, v184, v188, vcc quad_perm:[1,0,3,2] row_mask:0xf bank_mask:0xf
	s_nop 0
	v_cndmask_b32_dpp v187, v185, v189, vcc quad_perm:[1,0,3,2] row_mask:0xf bank_mask:0xf
	s_mov_b64 vcc, s[38:39]
	s_nop 0
	v_cndmask_b32_dpp v184, v188, v184, vcc quad_perm:[1,0,3,2] row_mask:0xf bank_mask:0xf
	v_cndmask_b32_dpp v185, v189, v185, vcc quad_perm:[1,0,3,2] row_mask:0xf bank_mask:0xf
	global_store_dwordx4 v252, v[184:187], s[76:77] offset:0
	v_cvt_pk_bf16_f32 v192, v192, v193
	v_cvt_pk_bf16_f32 v193, v194, v195
	v_cvt_pk_bf16_f32 v196, v196, v197
	s_mov_b64 vcc, s[36:37]
	v_cvt_pk_bf16_f32 v197, v198, v199
	v_cndmask_b32_dpp v194, v192, v196, vcc quad_perm:[1,0,3,2] row_mask:0xf bank_mask:0xf
	s_nop 0
	v_cndmask_b32_dpp v195, v193, v197, vcc quad_perm:[1,0,3,2] row_mask:0xf bank_mask:0xf
	s_mov_b64 vcc, s[38:39]
	s_nop 0
	v_cndmask_b32_dpp v192, v196, v192, vcc quad_perm:[1,0,3,2] row_mask:0xf bank_mask:0xf
	v_cndmask_b32_dpp v193, v197, v193, vcc quad_perm:[1,0,3,2] row_mask:0xf bank_mask:0xf
	global_store_dwordx4 v252, v[192:195], s[76:77] offset:1024
	v_cvt_pk_bf16_f32 v204, v204, v205
	v_cvt_pk_bf16_f32 v205, v206, v207
	v_cvt_pk_bf16_f32 v208, v208, v209
	s_mov_b64 vcc, s[36:37]
	v_cvt_pk_bf16_f32 v209, v210, v211
	v_cndmask_b32_dpp v206, v204, v208, vcc quad_perm:[1,0,3,2] row_mask:0xf bank_mask:0xf
	s_nop 0
	v_cndmask_b32_dpp v207, v205, v209, vcc quad_perm:[1,0,3,2] row_mask:0xf bank_mask:0xf
	s_mov_b64 vcc, s[38:39]
	s_nop 0
	v_cndmask_b32_dpp v204, v208, v204, vcc quad_perm:[1,0,3,2] row_mask:0xf bank_mask:0xf
	v_cndmask_b32_dpp v205, v209, v205, vcc quad_perm:[1,0,3,2] row_mask:0xf bank_mask:0xf
	global_store_dwordx4 v252, v[204:207], s[76:77] offset:2048
	v_cvt_pk_bf16_f32 v212, v212, v213
	v_cvt_pk_bf16_f32 v213, v214, v215
	v_cvt_pk_bf16_f32 v216, v216, v217
	s_mov_b64 vcc, s[36:37]
	v_cvt_pk_bf16_f32 v217, v218, v219
	v_cndmask_b32_dpp v214, v212, v216, vcc quad_perm:[1,0,3,2] row_mask:0xf bank_mask:0xf
	s_nop 0
	v_cndmask_b32_dpp v215, v213, v217, vcc quad_perm:[1,0,3,2] row_mask:0xf bank_mask:0xf
	s_mov_b64 vcc, s[38:39]
	s_nop 0
	v_cndmask_b32_dpp v212, v216, v212, vcc quad_perm:[1,0,3,2] row_mask:0xf bank_mask:0xf
	v_cndmask_b32_dpp v213, v217, v213, vcc quad_perm:[1,0,3,2] row_mask:0xf bank_mask:0xf
	global_store_dwordx4 v252, v[212:215], s[76:77] offset:3072
	s_add_u32 s76, s76, 0x1000
	s_addc_u32 s77, s77, 0
	v_cvt_pk_bf16_f32 v220, v220, v221
	v_cvt_pk_bf16_f32 v221, v222, v223
	v_cvt_pk_bf16_f32 v224, v224, v225
	s_mov_b64 vcc, s[36:37]
	v_cvt_pk_bf16_f32 v225, v226, v227
	v_cndmask_b32_dpp v222, v220, v224, vcc quad_perm:[1,0,3,2] row_mask:0xf bank_mask:0xf
	s_nop 0
	v_cndmask_b32_dpp v223, v221, v225, vcc quad_perm:[1,0,3,2] row_mask:0xf bank_mask:0xf
	s_mov_b64 vcc, s[38:39]
	s_nop 0
	v_cndmask_b32_dpp v220, v224, v220, vcc quad_perm:[1,0,3,2] row_mask:0xf bank_mask:0xf
	v_cndmask_b32_dpp v221, v225, v221, vcc quad_perm:[1,0,3,2] row_mask:0xf bank_mask:0xf
	global_store_dwordx4 v252, v[220:223], s[76:77] offset:0
	v_cvt_pk_bf16_f32 v228, v228, v229
	v_cvt_pk_bf16_f32 v229, v230, v231
	v_cvt_pk_bf16_f32 v232, v232, v233
	s_mov_b64 vcc, s[36:37]
	v_cvt_pk_bf16_f32 v233, v234, v235
	v_cndmask_b32_dpp v230, v228, v232, vcc quad_perm:[1,0,3,2] row_mask:0xf bank_mask:0xf
	s_nop 0
	v_cndmask_b32_dpp v231, v229, v233, vcc quad_perm:[1,0,3,2] row_mask:0xf bank_mask:0xf
	s_mov_b64 vcc, s[38:39]
	s_nop 0
	v_cndmask_b32_dpp v228, v232, v228, vcc quad_perm:[1,0,3,2] row_mask:0xf bank_mask:0xf
	v_cndmask_b32_dpp v229, v233, v229, vcc quad_perm:[1,0,3,2] row_mask:0xf bank_mask:0xf
	global_store_dwordx4 v252, v[228:231], s[76:77] offset:1024
	v_cvt_pk_bf16_f32 v236, v236, v237
	v_cvt_pk_bf16_f32 v237, v238, v239
	v_cvt_pk_bf16_f32 v240, v240, v241
	s_mov_b64 vcc, s[36:37]
	v_cvt_pk_bf16_f32 v241, v242, v243
	v_cndmask_b32_dpp v238, v236, v240, vcc quad_perm:[1,0,3,2] row_mask:0xf bank_mask:0xf
	s_nop 0
	v_cndmask_b32_dpp v239, v237, v241, vcc quad_perm:[1,0,3,2] row_mask:0xf bank_mask:0xf
	s_mov_b64 vcc, s[38:39]
	s_nop 0
	v_cndmask_b32_dpp v236, v240, v236, vcc quad_perm:[1,0,3,2] row_mask:0xf bank_mask:0xf
	v_cndmask_b32_dpp v237, v241, v237, vcc quad_perm:[1,0,3,2] row_mask:0xf bank_mask:0xf
	global_store_dwordx4 v252, v[236:239], s[76:77] offset:2048
	v_cvt_pk_bf16_f32 v244, v244, v245
	v_cvt_pk_bf16_f32 v245, v246, v247
	v_cvt_pk_bf16_f32 v248, v248, v249
	s_mov_b64 vcc, s[36:37]
	v_cvt_pk_bf16_f32 v249, v250, v251
	v_cndmask_b32_dpp v246, v244, v248, vcc quad_perm:[1,0,3,2] row_mask:0xf bank_mask:0xf
	s_nop 0
	v_cndmask_b32_dpp v247, v245, v249, vcc quad_perm:[1,0,3,2] row_mask:0xf bank_mask:0xf
	s_mov_b64 vcc, s[38:39]
	s_nop 0
	v_cndmask_b32_dpp v244, v248, v244, vcc quad_perm:[1,0,3,2] row_mask:0xf bank_mask:0xf
	v_cndmask_b32_dpp v245, v249, v245, vcc quad_perm:[1,0,3,2] row_mask:0xf bank_mask:0xf
	global_store_dwordx4 v252, v[244:247], s[76:77] offset:3072
